# scan stage (a): all 20 fragment reads deep-pipelined into free VGPRs with counted lgkmcnt
# speedup vs baseline: 1.0033x; 1.0033x over previous
.LBB0_474:
	v_ashrrev_i32_e32 v0, 6, v89
	v_lshrrev_b32_e32 v90, 4, v89
	v_lshlrev_b32_e32 v74, 8, v92
	v_lshl_add_u32 v93, v0, 12, 0
	v_bitop3_b32 v75, v90, v92, 3 bitop3:0x6c
	v_add_u32_e32 v91, v93, v74
	v_lshlrev_b32_e32 v75, 4, v75
	v_add_u32_e32 v76, v91, v75
	ds_read_b128 v[82:85], v76
	v_add_u32_e32 v118, 0, v74
	v_add_u32_e32 v144, v118, v75
	ds_read_b128 v[128:131], v144 offset:16384
	ds_read_b128 v[132:135], v144 offset:20480
	ds_read_b128 v[136:139], v144 offset:24576
	ds_read_b128 v[140:143], v144 offset:28672
	v_bfe_u32 v119, v89, 4, 2
	v_bitop3_b32 v77, v119, v92, 4 bitop3:0x36
	v_lshlrev_b32_e32 v77, 4, v77
	v_add_u32_e32 v80, v91, v77
	ds_read_b128 v[110:113], v80
	v_add_u32_e32 v146, v118, v77
	ds_read_b128 v[150:153], v146 offset:16384
	ds_read_b128 v[154:157], v146 offset:20480
	ds_read_b128 v[158:161], v146 offset:24576
	ds_read_b128 v[162:165], v146 offset:28672
	v_bitop3_b32 v78, v119, v92, 8 bitop3:0x36
	v_lshlrev_b32_e32 v78, 4, v78
	v_add_u32_e32 v81, v91, v78
	ds_read_b128 v[114:117], v81
	v_add_u32_e32 v147, v118, v78
	v_bitop3_b32 v79, v119, v92, 12 bitop3:0x36
	v_lshlrev_b32_e32 v79, 4, v79
	v_add_u32_e32 v120, v91, v79
	v_add_u32_e32 v167, v118, v79
	v_lshrrev_b32_e32 v89, 3, v89
	s_and_b32 s1, s29, 0x2000
	s_add_i32 s1, s1, 0
	s_mov_b64 s[16:17], -1
	s_waitcnt lgkmcnt(9)
	v_mfma_f32_16x16x32_bf16 v[94:97], v[82:85], v[128:131], 0
	ds_read_b128 v[128:131], v147 offset:16384
	s_waitcnt lgkmcnt(9)
	v_mfma_f32_16x16x32_bf16 v[102:105], v[82:85], v[132:135], 0
	ds_read_b128 v[132:135], v147 offset:20480
	s_waitcnt lgkmcnt(9)
	v_mfma_f32_16x16x32_bf16 v[98:101], v[82:85], v[136:139], 0
	ds_read_b128 v[136:139], v147 offset:24576
	s_waitcnt lgkmcnt(9)
	v_mfma_f32_16x16x32_bf16 v[106:109], v[82:85], v[140:143], 0
	ds_read_b128 v[140:143], v147 offset:28672
	ds_read_b128 v[82:85], v120
	s_waitcnt lgkmcnt(9)
	v_mfma_f32_16x16x32_bf16 v[94:97], v[110:113], v[150:153], v[94:97]
	ds_read_b128 v[150:153], v167 offset:16384
	s_waitcnt lgkmcnt(9)
	v_mfma_f32_16x16x32_bf16 v[102:105], v[110:113], v[154:157], v[102:105]
	ds_read_b128 v[154:157], v167 offset:20480
	s_waitcnt lgkmcnt(9)
	v_mfma_f32_16x16x32_bf16 v[98:101], v[110:113], v[158:161], v[98:101]
	ds_read_b128 v[158:161], v167 offset:24576
	s_waitcnt lgkmcnt(9)
	v_mfma_f32_16x16x32_bf16 v[106:109], v[110:113], v[162:165], v[106:109]
	ds_read_b128 v[162:165], v167 offset:28672
	s_waitcnt lgkmcnt(8)
	v_mfma_f32_16x16x32_bf16 v[94:97], v[114:117], v[128:131], v[94:97]
	s_waitcnt lgkmcnt(7)
	v_mfma_f32_16x16x32_bf16 v[102:105], v[114:117], v[132:135], v[102:105]
	s_waitcnt lgkmcnt(6)
	v_mfma_f32_16x16x32_bf16 v[98:101], v[114:117], v[136:139], v[98:101]
	s_waitcnt lgkmcnt(5)
	v_mfma_f32_16x16x32_bf16 v[106:109], v[114:117], v[140:143], v[106:109]
	s_waitcnt lgkmcnt(3)
	v_mfma_f32_16x16x32_bf16 v[94:97], v[82:85], v[150:153], v[94:97]
	s_waitcnt lgkmcnt(2)
	v_mfma_f32_16x16x32_bf16 v[102:105], v[82:85], v[154:157], v[102:105]
	s_waitcnt lgkmcnt(1)
	v_mfma_f32_16x16x32_bf16 v[98:101], v[82:85], v[158:161], v[98:101]
	s_waitcnt lgkmcnt(0)
	v_mfma_f32_16x16x32_bf16 v[106:109], v[82:85], v[162:165], v[106:109]
	v_add_u32_e32 v91, v118, v79
	v_lshlrev_b32_e32 v83, 2, v119
	v_lshl_or_b32 v82, v0, 4, v83
	v_lshrrev_b32_e32 v84, 3, v92
	v_lshrrev_b32_e32 v85, 1, v83
	v_xor_b32_e32 v85, v85, v84
	v_lshlrev_b32_e32 v85, 4, v85
	v_lshl_add_u32 v84, v82, 7, v85
	v_add_u32_e32 v84, v84, v87
	v_xor_b32_e32 v85, 16, v84
	v_add_u32_e32 v85, 0x100, v85
	v_sub_u32_e32 v112, v92, v82
	v_sub_u32_e32 v113, 0, v112
	v_cndmask_b32_e64 v112, v113, v112, s[4:5]
	v_mov_b32_e32 v113, -16
	v_cndmask_b32_e64 v113, v113, 16, s[4:5]
	v_mov_b32_e32 v114, -1
	v_cndmask_b32_e64 v114, v114, 1, s[4:5]
	v_add_u32_e32 v115, v114, v114
	v_add_u32_e32 v116, v115, v114
	v_cmp_ge_i32_e64 s[98:99], 0, v112
	v_cmp_le_i32_e64 s[100:101], v112, v114
	v_cmp_le_i32_e32 vcc, v112, v115
	v_cndmask_b32_e64 v94, 0, v94, s[98:99]
	v_cndmask_b32_e64 v95, 0, v95, s[100:101]
	v_cmp_le_i32_e64 s[98:99], v112, v116
	v_cndmask_b32_e32 v96, 0, v96, vcc
	v_cvt_pk_bf16_f32 v94, v94, v95
	v_cndmask_b32_e64 v97, 0, v97, s[98:99]
	v_cvt_pk_bf16_f32 v96, v96, v97
	ds_write_b16 v84, v94 offset:53248
	ds_write_b16_d16_hi v84, v94 offset:53376
	ds_write_b16 v85, v96 offset:53248
	ds_write_b16_d16_hi v85, v96 offset:53376
	v_add_u32_e32 v112, v112, v113
	v_xor_b32_e32 v91, 0x20, v84
	v_xor_b32_e32 v110, 0x20, v85
	v_cmp_ge_i32_e64 s[98:99], 0, v112
	v_cmp_le_i32_e64 s[100:101], v112, v114
	v_cmp_le_i32_e32 vcc, v112, v115
	v_cndmask_b32_e64 v102, 0, v102, s[98:99]
	v_cndmask_b32_e64 v103, 0, v103, s[100:101]
	v_cmp_le_i32_e64 s[98:99], v112, v116
	v_cndmask_b32_e32 v104, 0, v104, vcc
	v_cvt_pk_bf16_f32 v102, v102, v103
	v_cndmask_b32_e64 v105, 0, v105, s[98:99]
	v_cvt_pk_bf16_f32 v104, v104, v105
	ds_write_b16 v91, v102 offset:53248
	ds_write_b16_d16_hi v91, v102 offset:53376
	ds_write_b16 v110, v104 offset:53248
	ds_write_b16_d16_hi v110, v104 offset:53376
	v_add_u32_e32 v112, v112, v113
	v_xor_b32_e32 v91, 0x40, v84
	v_xor_b32_e32 v110, 0x40, v85
	v_cmp_ge_i32_e64 s[98:99], 0, v112
	v_cmp_le_i32_e64 s[100:101], v112, v114
	v_cmp_le_i32_e32 vcc, v112, v115
	v_cndmask_b32_e64 v98, 0, v98, s[98:99]
	v_cndmask_b32_e64 v99, 0, v99, s[100:101]
	v_cmp_le_i32_e64 s[98:99], v112, v116
	v_cndmask_b32_e32 v100, 0, v100, vcc
	v_cvt_pk_bf16_f32 v98, v98, v99
	v_cndmask_b32_e64 v101, 0, v101, s[98:99]
	v_cvt_pk_bf16_f32 v100, v100, v101
	ds_write_b16 v91, v98 offset:53248
	ds_write_b16_d16_hi v91, v98 offset:53376
	ds_write_b16 v110, v100 offset:53248
	ds_write_b16_d16_hi v110, v100 offset:53376
	v_add_u32_e32 v112, v112, v113
	v_xor_b32_e32 v91, 0x60, v84
	v_xor_b32_e32 v110, 0x60, v85
	v_cmp_ge_i32_e64 s[98:99], 0, v112
	v_cmp_le_i32_e64 s[100:101], v112, v114
	v_cmp_le_i32_e32 vcc, v112, v115
	v_cndmask_b32_e64 v106, 0, v106, s[98:99]
	v_cndmask_b32_e64 v107, 0, v107, s[100:101]
	v_cmp_le_i32_e64 s[98:99], v112, v116
	v_cndmask_b32_e32 v108, 0, v108, vcc
	v_cvt_pk_bf16_f32 v106, v106, v107
	v_cndmask_b32_e64 v109, 0, v109, s[98:99]
	v_cvt_pk_bf16_f32 v108, v108, v109
	ds_write_b16 v91, v106 offset:53248
	ds_write_b16_d16_hi v91, v106 offset:53376
	ds_write_b16 v110, v108 offset:53248
	ds_write_b16_d16_hi v110, v108 offset:53376
	v_lshlrev_b32_e32 v111, 7, v92
	v_bitop3_b32 v89, v90, v88, 3 bitop3:0x6c
	s_add_i32 s0, 0, 0x13000
	v_lshlrev_b32_e32 v84, 7, v0
	v_lshlrev_b32_e32 v85, 2, v92
	v_add3_u32 v84, s0, v84, v85
	ds_read2_b32 v[84:85], v84 offset1:16
	v_add_u32_e32 v112, 0, v111
	v_lshlrev_b32_e32 v113, 4, v89
	v_add_u32_e32 v114, v112, v113
	ds_read_b128 v[94:97], v114 offset:49152
	s_waitcnt lgkmcnt(1)
	v_pk_mul_f32 v[40:41], v[40:41], v[84:85] op_sel_hi:[1,0]
	v_pk_mul_f32 v[38:39], v[38:39], v[84:85] op_sel_hi:[1,0]
	v_pk_mul_f32 v[48:49], v[48:49], v[84:85] op_sel_hi:[1,0]
	v_pk_mul_f32 v[46:47], v[46:47], v[84:85] op_sel_hi:[1,0]
	v_bitop3_b32 v84, v119, v88, 4 bitop3:0x36
	v_add3_u32 v89, v93, v113, v111
	v_lshlrev_b32_e32 v84, 4, v84
	ds_read_b128 v[98:101], v89 offset:32768
	ds_read_b128 v[102:105], v114 offset:51200
	ds_read_b128 v[106:109], v89 offset:34816
	v_mov_b32_e32 v110, v85
	v_add_u32_e32 v85, v112, v84
	ds_read_b128 v[88:91], v85 offset:49152
	v_pk_mul_f32 v[44:45], v[44:45], v[110:111] op_sel_hi:[1,0]
	v_pk_mul_f32 v[42:43], v[42:43], v[110:111] op_sel_hi:[1,0]
	v_pk_mul_f32 v[52:53], v[52:53], v[110:111] op_sel_hi:[1,0]
	v_pk_mul_f32 v[50:51], v[50:51], v[110:111] op_sel_hi:[1,0]
	v_add3_u32 v93, v93, v84, v111
	s_waitcnt lgkmcnt(3)
	v_mfma_f32_16x16x32_bf16 v[38:41], v[94:97], v[98:101], v[38:41]
	s_add_i32 s0, s29, 0xffffe000
	s_and_b32 s0, s0, 0x2000
	s_andn2_b64 vcc, exec, s[8:9]
	s_waitcnt lgkmcnt(1)
	v_mfma_f32_16x16x32_bf16 v[42:45], v[94:97], v[106:109], v[42:45]
	v_mfma_f32_16x16x32_bf16 v[46:49], v[102:105], v[98:101], v[46:49]
	v_mfma_f32_16x16x32_bf16 v[50:53], v[102:105], v[106:109], v[50:53]
	ds_read_b128 v[94:97], v93 offset:32768
	ds_read_b128 v[98:101], v85 offset:51200
	ds_read_b128 v[102:105], v93 offset:34816
	s_waitcnt lgkmcnt(2)
	v_mfma_f32_16x16x32_bf16 v[38:41], v[88:91], v[94:97], v[38:41]
	s_waitcnt lgkmcnt(0)
	v_mfma_f32_16x16x32_bf16 v[42:45], v[88:91], v[102:105], v[42:45]
	v_lshl_or_b32 v88, v0, 5, v92
	v_lshrrev_b32_e32 v88, 3, v88
	v_or_b32_e32 v89, 1, v83
	v_mfma_f32_16x16x32_bf16 v[46:49], v[98:101], v[94:97], v[46:49]
	v_xor_b32_e32 v95, v88, v83
	v_lshlrev_b32_e32 v95, 4, v95
	v_lshlrev_b32_e32 v94, 10, v119
	v_add3_u32 v95, s1, v95, v87
	v_bitop3_b32 v97, v83, v88, 1 bitop3:0x36
	v_cvt_pk_bf16_f32 v93, v38, s0
	v_add_u32_e32 v96, v95, v94
	v_lshlrev_b32_e32 v97, 4, v97
	ds_write_b16 v96, v93 offset:61440
	v_lshlrev_b32_e32 v96, 8, v89
	v_add3_u32 v97, s1, v97, v87
	v_mfma_f32_16x16x32_bf16 v[50:53], v[98:101], v[102:105], v[50:53]
	v_cvt_pk_bf16_f32 v93, v39, s0
	v_add_u32_e32 v98, v97, v96
	ds_write_b16 v98, v93 offset:61440
	v_bitop3_b32 v98, v83, v88, 2 bitop3:0x36
	v_or_b32_e32 v90, 2, v83
	v_lshlrev_b32_e32 v98, 4, v98
	v_lshlrev_b32_e32 v90, 8, v90
	v_add3_u32 v98, s1, v98, v87
	v_bitop3_b32 v100, v83, v88, 3 bitop3:0x36
	v_or_b32_e32 v91, 3, v83
	v_cvt_pk_bf16_f32 v93, v40, s0
	v_add_u32_e32 v99, v98, v90
	v_lshlrev_b32_e32 v100, 4, v100
	ds_write_b16 v99, v93 offset:61440
	v_lshlrev_b32_e32 v99, 8, v91
	v_add3_u32 v100, s1, v100, v87
	v_cvt_pk_bf16_f32 v93, v41, s0
	v_add_u32_e32 v101, v100, v99
	ds_write_b16 v101, v93 offset:61440
	v_bitop3_b32 v101, v88, v83, 2 bitop3:0x36
	v_lshlrev_b32_e32 v101, 4, v101
	v_bitop3_b32 v89, v88, v89, 2 bitop3:0x36
	v_add3_u32 v101, s1, v101, v87
	v_lshlrev_b32_e32 v89, 4, v89
	v_bitop3_b32 v83, v88, v83, 2 bitop3:0x14
	v_cvt_pk_bf16_f32 v93, v42, s0
	v_add_u32_e32 v102, v101, v94
	v_add3_u32 v89, s1, v89, v87
	v_lshlrev_b32_e32 v83, 4, v83
	v_bitop3_b32 v88, v88, v91, 2 bitop3:0x36
	ds_write_b16 v102, v93 offset:61440
	v_cvt_pk_bf16_f32 v93, v43, s0
	v_add_u32_e32 v96, v89, v96
	v_add3_u32 v83, s1, v83, v87
	v_lshlrev_b32_e32 v88, 4, v88
	ds_write_b16 v96, v93 offset:61440
	v_cvt_pk_bf16_f32 v93, v44, s0
	v_add_u32_e32 v90, v83, v90
	v_add3_u32 v87, s1, v88, v87
	ds_write_b16 v90, v93 offset:61440
	v_cvt_pk_bf16_f32 v90, v45, s0
	v_add_u32_e32 v88, v87, v99
	ds_write_b16 v88, v90 offset:61440
	v_or_b32_e32 v90, 0x1000, v94
	v_cvt_pk_bf16_f32 v88, v46, s0
	v_add_u32_e32 v91, v95, v90
	ds_write_b16 v91, v88 offset:61440
	v_or_b32_e32 v91, 0x1100, v94
	v_cvt_pk_bf16_f32 v88, v47, s0
	v_add_u32_e32 v93, v97, v91
	ds_write_b16 v93, v88 offset:61440
	v_or_b32_e32 v93, 0x1200, v94
	v_cvt_pk_bf16_f32 v88, v48, s0
	v_add_u32_e32 v95, v98, v93
	v_or_b32_e32 v94, 0x1300, v94
	ds_write_b16 v95, v88 offset:61440
	v_cvt_pk_bf16_f32 v88, v49, s0
	v_add_u32_e32 v95, v100, v94
	ds_write_b16 v95, v88 offset:61440
	v_cvt_pk_bf16_f32 v88, v50, s0
	v_add_u32_e32 v90, v101, v90
	ds_write_b16 v90, v88 offset:61440
	v_cvt_pk_bf16_f32 v88, v51, s0
	v_add_u32_e32 v89, v89, v91
	ds_write_b16 v89, v88 offset:61440
	v_cvt_pk_bf16_f32 v88, v52, s0
	v_add_u32_e32 v83, v83, v93
	ds_write_b16 v83, v88 offset:61440
	v_cvt_pk_bf16_f32 v83, v53, s0
	v_add_u32_e32 v87, v87, v94
	ds_write_b16 v87, v83 offset:61440
	s_waitcnt lgkmcnt(0)
	s_barrier
	ds_read_b128 v[88:91], v76
	s_add_i32 s0, s0, 0
	v_add_u32_e32 v83, s0, v74
	v_add_u32_e32 v74, v83, v75
	ds_read_b128 v[94:97], v74 offset:61440
	v_add_u32_e32 v74, 0xf000, v74
	ds_read_b128 v[98:101], v74 offset:4096
	ds_read_b128 v[102:105], v80
	v_add_u32_e32 v80, v83, v77
	ds_read_b128 v[74:77], v80 offset:61440
	s_waitcnt lgkmcnt(3)
	v_mfma_f32_16x16x32_bf16 v[94:97], v[88:91], v[94:97], 0
	v_add_u32_e32 v78, v83, v78
	ds_read_b128 v[106:109], v78 offset:61440
	v_add_u32_e32 v80, 0xf000, v80
	s_waitcnt lgkmcnt(3)
	v_mfma_f32_16x16x32_bf16 v[88:91], v[88:91], v[98:101], 0
	ds_read_b128 v[98:101], v80 offset:4096
	v_add_u32_e32 v78, 0xf000, v78
	v_add_u32_e32 v83, v83, v79
	s_waitcnt lgkmcnt(2)
	v_mfma_f32_16x16x32_bf16 v[74:77], v[102:105], v[74:77], v[94:97]
	v_lshl_add_u32 v0, v0, 11, v112
	s_nop 1
	ds_read_b128 v[94:97], v81
	s_waitcnt lgkmcnt(1)
	v_mfma_f32_16x16x32_bf16 v[88:91], v[102:105], v[98:101], v[88:91]
	ds_read_b128 v[98:101], v78 offset:4096
	ds_read_b128 v[102:105], v120
	ds_read_b128 v[78:81], v83 offset:61440
	v_add_u32_e32 v83, 0xf000, v83
	s_waitcnt lgkmcnt(3)
	v_mfma_f32_16x16x32_bf16 v[74:77], v[94:97], v[106:109], v[74:77]
	s_waitcnt lgkmcnt(2)
	v_mfma_f32_16x16x32_bf16 v[88:91], v[94:97], v[98:101], v[88:91]
	ds_read_b128 v[94:97], v83 offset:4096
	s_waitcnt lgkmcnt(1)
	v_mfma_f32_16x16x32_bf16 v[74:77], v[102:105], v[78:81], v[74:77]
	v_add_u32_e32 v78, v0, v113
	ds_read_b128 v[78:81], v78 offset:53248
	ds_read_b128 v[98:101], v114 offset:49152
	v_add_u32_e32 v0, v0, v84
	s_waitcnt lgkmcnt(2)
	v_mfma_f32_16x16x32_bf16 v[88:91], v[102:105], v[94:97], v[88:91]
	ds_read_b128 v[94:97], v114 offset:51200
	ds_read_b128 v[102:105], v0 offset:53248
	v_cndmask_b32_e64 v0, 0, 1, s[8:9]
	s_waitcnt lgkmcnt(2)
	v_mfma_f32_16x16x32_bf16 v[74:77], v[78:81], v[98:101], v[74:77]
	v_add_u32_e32 v84, s30, v82
	v_cmp_ne_u32_e64 s[6:7], 1, v0
	s_waitcnt lgkmcnt(1)
	v_mfma_f32_16x16x32_bf16 v[88:91], v[78:81], v[94:97], v[88:91]
	ds_read_b128 v[78:81], v85 offset:49152
	ds_read_b128 v[94:97], v85 offset:51200
	s_waitcnt lgkmcnt(1)
	v_mfma_f32_16x16x32_bf16 v[78:81], v[102:105], v[78:81], v[74:77]
	s_waitcnt lgkmcnt(0)
	v_mfma_f32_16x16x32_bf16 v[74:77], v[102:105], v[94:97], v[88:91]
	s_cbranch_vccnz .LBB0_476
	v_ashrrev_i32_e32 v82, 1, v84
	v_ashrrev_i32_e32 v83, 31, v82
	v_lshlrev_b64 v[82:83], 12, v[82:83]
	v_lshl_add_u64 v[82:83], s[12:13], 0, v[82:83]
	s_mov_b64 s[16:17], 0
